# attention phase B: priority raised from the tile staging (waits and writes) through the compute core, lowered for the next register-stage loads
# speedup vs baseline: 1.0010x; 1.0010x over previous
.LBB0_546:
	s_cmp_eq_u32 s77, 1
	s_cselect_b32 s0, 2, 4
	s_lshr_b32 s1, 16, s0
	s_lshl_b32 s18, s67, 6
	s_setprio 1
	s_waitcnt vmcnt(14) lgkmcnt(2)
	ds_write_b128 v219, v[12:15]
	s_waitcnt vmcnt(12)
	ds_write_b128 v219, v[24:27] offset:1152
	s_waitcnt vmcnt(10)
	ds_write_b128 v219, v[32:35] offset:2304
	s_waitcnt vmcnt(8)
	ds_write_b128 v219, v[40:43] offset:3456
	s_waitcnt vmcnt(6)
	ds_write_b128 v219, v[52:55] offset:4608
	s_waitcnt vmcnt(4)
	ds_write_b128 v219, v[64:67] offset:5760
	s_waitcnt vmcnt(2)
	ds_write_b128 v219, v[76:79] offset:6912
	s_waitcnt vmcnt(0)
	ds_write_b128 v219, v[88:91] offset:8064
	s_waitcnt lgkmcnt(8)
	ds_write_b128 v220, v[4:7] offset:9216
	ds_write_b128 v220, v[8:11] offset:10240
	ds_write_b128 v220, v[16:19] offset:11264
	ds_write_b128 v220, v[20:23] offset:12288
	ds_write_b128 v220, v[28:31] offset:13312
	ds_write_b128 v220, v[36:39] offset:14336
	ds_write_b128 v220, v[44:47] offset:15360
	ds_write_b128 v220, v[68:71] offset:16384
	v_mul_u32_u24_e32 v2, s1, v173
	s_sub_i32 s16, 0x80, s18
	s_lshr_b32 s0, s8, s0
	v_mov_b32_e32 v3, s16
	s_sub_i32 s19, s16, s0
	v_subrev_u32_e32 v2, s18, v2
	v_add_u32_e32 v228, v207, v192
	v_add_u32_e32 v230, v207, v194
	v_mad_u32_u24 v18, s1, v173, v3
	s_cmp_lg_u32 s77, 2
	v_max_i32_e32 v19, s19, v2
	v_add_u32_e32 v229, v207, v193
	ds_read_b128 v[10:13], v228 offset:9216
	ds_read_b128 v[14:17], v229 offset:9216
	v_add_u32_e32 v231, v207, v195
	ds_read_b128 v[6:9], v230 offset:9728
	ds_read_b128 v[2:5], v231 offset:9728
	s_cselect_b64 s[0:1], -1, 0
	s_cmp_lg_u32 s67, 2
	s_cselect_b64 s[16:17], -1, 0
	s_or_b64 s[0:1], s[16:17], s[0:1]
	v_sub_u32_e32 v18, v18, v19
	v_sub_u32_e32 v25, v176, v19
	s_mov_b64 s[16:17], -1
	s_and_b64 vcc, exec, s[0:1]
	v_add_u32_e32 v225, s45, v175
	v_cmp_le_u32_e64 s[0:1], v25, v18
	v_add_u32_e32 v26, 1, v25
	v_add_u32_e32 v24, 2, v25
	v_add_u32_e32 v23, 3, v25
	v_add_u32_e32 v22, 4, v25
	v_add_u32_e32 v21, 5, v25
	v_add_u32_e32 v20, 6, v25
	v_add_u32_e32 v19, 7, v25
	s_cbranch_vccz .LBB0_548
	s_waitcnt vmcnt(1) lgkmcnt(3)
	v_mfma_f32_16x16x32_bf16 v[28:31], v[10:13], v[132:135], 0
	ds_read_b128 v[32:35], v228 offset:13312
	ds_read_b128 v[36:39], v229 offset:13312
	v_cmp_le_u32_e32 vcc, v26, v18
	ds_read_b128 v[40:43], v230 offset:13824
	ds_read_b128 v[44:47], v231 offset:13824
	s_waitcnt vmcnt(0) lgkmcnt(6)
	v_mfma_f32_16x16x32_bf16 v[28:31], v[14:17], v[136:139], v[28:31]
	s_mov_b64 s[16:17], 0
	s_waitcnt lgkmcnt(5)
	v_mfma_f32_16x16x32_bf16 v[52:55], v[6:9], v[132:135], 0
	s_waitcnt lgkmcnt(4)
	v_mfma_f32_16x16x32_bf16 v[52:55], v[2:5], v[136:139], v[52:55]
	s_nop 2
	v_cndmask_b32_e32 v64, v217, v29, vcc
	v_cmp_le_u32_e32 vcc, v24, v18
	v_cndmask_b32_e64 v27, v217, v28, s[0:1]
	s_nop 0
	v_cndmask_b32_e32 v65, v217, v30, vcc
	v_cmp_le_u32_e32 vcc, v23, v18
	s_nop 1
	v_cndmask_b32_e32 v66, v217, v31, vcc
	s_waitcnt lgkmcnt(3)
	v_mfma_f32_16x16x32_bf16 v[28:31], v[32:35], v[132:135], 0
	v_cmp_le_u32_e32 vcc, v22, v18
	s_nop 1
	v_cndmask_b32_e32 v52, v217, v52, vcc
	v_cmp_le_u32_e32 vcc, v21, v18
	s_waitcnt lgkmcnt(2)
	v_mfma_f32_16x16x32_bf16 v[28:31], v[36:39], v[136:139], v[28:31]
	v_add_u32_e32 v37, 32, v25
	v_cndmask_b32_e32 v53, v217, v53, vcc
	v_cmp_le_u32_e32 vcc, v20, v18
	s_waitcnt lgkmcnt(1)
	v_mfma_f32_16x16x32_bf16 v[32:35], v[40:43], v[132:135], 0
	v_cndmask_b32_e32 v54, v217, v54, vcc
	v_cmp_le_u32_e32 vcc, v19, v18
	s_waitcnt lgkmcnt(0)
	v_mfma_f32_16x16x32_bf16 v[32:35], v[44:47], v[136:139], v[32:35]
	v_cndmask_b32_e32 v36, v217, v55, vcc
	v_cmp_le_u32_e32 vcc, v37, v18
	v_add_u32_e32 v37, 33, v25
	s_nop 0
	v_cndmask_b32_e32 v28, v217, v28, vcc
	v_cmp_le_u32_e32 vcc, v37, v18
	v_add_u32_e32 v37, 34, v25
	s_nop 0
	v_cndmask_b32_e32 v29, v217, v29, vcc
	v_cmp_le_u32_e32 vcc, v37, v18
	v_add_u32_e32 v37, 35, v25
	s_nop 0
	v_cndmask_b32_e32 v30, v217, v30, vcc
	v_cmp_le_u32_e32 vcc, v37, v18
	v_add_u32_e32 v37, 36, v25
	s_nop 0
	v_cndmask_b32_e32 v31, v217, v31, vcc
	v_cmp_le_u32_e32 vcc, v37, v18
	v_add_u32_e32 v37, 37, v25
	s_nop 0
	v_cndmask_b32_e32 v32, v217, v32, vcc
	v_cmp_le_u32_e32 vcc, v37, v18
	v_add_u32_e32 v37, 38, v25
	s_nop 0
	v_cndmask_b32_e32 v33, v217, v33, vcc
	v_cmp_le_u32_e32 vcc, v37, v18
	v_add_u32_e32 v37, 39, v25
	s_nop 0
	v_cndmask_b32_e32 v34, v217, v34, vcc
	v_cmp_le_u32_e32 vcc, v37, v18
	v_max3_f32 v37, v27, s62, v64
	v_max3_f32 v37, v37, v65, v66
	v_max3_f32 v37, v37, v52, v53
	v_max3_f32 v37, v37, v54, v36
	v_max3_f32 v37, v37, v28, v29
	v_max3_f32 v37, v37, v30, v31
	v_cndmask_b32_e32 v35, v217, v35, vcc
	v_max3_f32 v37, v37, v32, v33
	v_max3_f32 v37, v37, v34, v35
	ds_bpermute_b32 v38, v0, v37
	s_waitcnt lgkmcnt(0)
	v_max_f32_e32 v38, v38, v38
	v_max_f32_e32 v37, v37, v38
	ds_bpermute_b32 v38, v222, v37
	s_waitcnt lgkmcnt(0)
	v_max3_f32 v226, v223, v37, v38
	v_sub_f32_e32 v27, v27, v226
	v_exp_f32_e32 v27, v27
	v_sub_f32_e32 v38, v64, v226
	v_exp_f32_e32 v38, v38
	v_sub_f32_e32 v39, v65, v226
	v_sub_f32_e32 v28, v28, v226
	v_exp_f32_e32 v39, v39
	v_sub_f32_e32 v40, v66, v226
	v_exp_f32_e32 v90, v28
	v_sub_f32_e32 v28, v29, v226
	v_exp_f32_e32 v40, v40
	v_sub_f32_e32 v42, v52, v226
	v_exp_f32_e32 v91, v28
	v_sub_f32_e32 v28, v30, v226
	v_add_f32_e32 v41, 0, v27
	v_exp_f32_e32 v42, v42
	v_sub_f32_e32 v43, v53, v226
	v_exp_f32_e32 v156, v28
	v_sub_f32_e32 v28, v31, v226
	v_add_f32_e32 v41, v38, v41
	v_exp_f32_e32 v43, v43
	v_sub_f32_e32 v44, v54, v226
	v_exp_f32_e32 v160, v28
	v_sub_f32_e32 v28, v32, v226
	v_add_f32_e32 v41, v39, v41
	v_exp_f32_e32 v44, v44
	v_sub_f32_e32 v36, v36, v226
	v_exp_f32_e32 v161, v28
	v_sub_f32_e32 v28, v33, v226
	v_sub_f32_e32 v37, v223, v226
	v_add_f32_e32 v41, v40, v41
	v_exp_f32_e32 v36, v36
	v_exp_f32_e32 v162, v28
	v_sub_f32_e32 v28, v34, v226
	v_add_f32_e32 v41, v42, v41
	v_exp_f32_e32 v164, v28
	v_sub_f32_e32 v64, v35, v226
	v_exp_f32_e32 v88, v37
	v_cvt_pk_bf16_f32 v28, v27, v38
	v_cvt_pk_bf16_f32 v29, v39, v40
	v_cvt_pk_bf16_f32 v30, v42, v43
	v_cvt_pk_bf16_f32 v31, v44, v36
	ds_read_b64_tr_b16 v[34:35], v225 offset:576
	ds_read_b64_tr_b16 v[32:33], v225
	v_add_f32_e32 v41, v43, v41
	v_add_f32_e32 v41, v44, v41
	v_add_f32_e32 v89, v36, v41
	ds_read_b64_tr_b16 v[42:43], v225 offset:608
	ds_read_b64_tr_b16 v[40:41], v225 offset:32
	ds_read_b64_tr_b16 v[44:45], v225 offset:64
	ds_read_b64_tr_b16 v[52:53], v225 offset:96
	ds_read_b64_tr_b16 v[46:47], v225 offset:640
	ds_read_b64_tr_b16 v[54:55], v225 offset:672
	v_pk_mul_f32 v[38:39], v[154:155], v[88:89] op_sel_hi:[1,0]
	v_pk_mul_f32 v[36:37], v[152:153], v[88:89] op_sel_hi:[1,0]
	v_exp_f32_e32 v27, v64
	v_pk_mul_f32 v[66:67], v[142:143], v[88:89] op_sel_hi:[1,0]
	s_waitcnt lgkmcnt(6)
	v_mfma_f32_16x16x32_bf16 v[32:35], v[32:35], v[28:31], v[36:39]
	v_mul_f32_e64 v64, v140, v88
	v_mul_f32_e64 v65, v141, v88
	s_nop 0
	v_pk_mul_f32 v[38:39], v[150:151], v[88:89] op_sel_hi:[1,0]
	v_pk_mul_f32 v[36:37], v[148:149], v[88:89] op_sel_hi:[1,0]
	s_waitcnt lgkmcnt(4)
	s_nop 0
	v_mfma_f32_16x16x32_bf16 v[36:39], v[40:43], v[28:31], v[36:39]
	v_mul_f32_e64 v42, v146, v88
	v_mul_f32_e64 v43, v147, v88
	v_pk_mul_f32 v[40:41], v[144:145], v[88:89] op_sel_hi:[1,0]
	s_waitcnt lgkmcnt(1)
	s_nop 0
	v_mfma_f32_16x16x32_bf16 v[40:43], v[44:47], v[28:31], v[40:43]
	v_cvt_pk_bf16_f32 v44, v90, v91
	v_cvt_pk_bf16_f32 v45, v156, v160
	v_cvt_pk_bf16_f32 v46, v161, v162
	v_cvt_pk_bf16_f32 v47, v164, v27
	ds_read_b64_tr_b16 v[70:71], v225 offset:5184
	ds_read_b64_tr_b16 v[68:69], v225 offset:4608
	s_waitcnt lgkmcnt(0)
	v_mfma_f32_16x16x32_bf16 v[168:171], v[68:71], v[44:47], v[32:35]
	s_nop 2
	v_add_f32_e32 v32, v90, v89
	v_add_f32_e32 v32, v91, v32
	v_add_f32_e32 v32, v156, v32
	v_mfma_f32_16x16x32_bf16 v[28:31], v[52:55], v[28:31], v[64:67]
	ds_read_b64_tr_b16 v[54:55], v225 offset:5216
	ds_read_b64_tr_b16 v[52:53], v225 offset:4640
	s_nop 0
	ds_read_b64_tr_b16 v[64:65], v225 offset:4672
	ds_read_b64_tr_b16 v[76:77], v225 offset:4704
	ds_read_b64_tr_b16 v[66:67], v225 offset:5248
	ds_read_b64_tr_b16 v[78:79], v225 offset:5280
	v_add_f32_e32 v32, v160, v32
	v_add_f32_e32 v32, v161, v32
	v_add_f32_e32 v32, v162, v32
	s_waitcnt lgkmcnt(0)
	v_add_f32_e32 v32, v164, v32
	v_add_f32_e32 v227, v27, v32
	s_waitcnt lgkmcnt(4)
	v_mfma_f32_16x16x32_bf16 v[156:159], v[52:55], v[44:47], v[36:39]
	v_fmac_f32_e32 v227, v224, v88
	s_waitcnt lgkmcnt(1)
	v_mfma_f32_16x16x32_bf16 v[160:163], v[64:67], v[44:47], v[40:43]
	s_waitcnt lgkmcnt(0)
	v_mfma_f32_16x16x32_bf16 v[164:167], v[76:79], v[44:47], v[28:31]

.LBB0_555:
	s_add_i32 s67, s67, 1
	s_and_b64 s[0:1], s[38:39], exec
	s_cselect_b32 s14, s66, s67
	s_and_b64 s[0:1], s[18:19], exec
	s_cselect_b32 s78, s67, s14
	s_xor_b64 s[0:1], s[18:19], -1
	v_cndmask_b32_e64 v2, 0, 1, s[0:1]
	s_setprio 1
	s_waitcnt vmcnt(32)
	ds_write_b128 v219, v[48:51]
	s_waitcnt vmcnt(30)
	ds_write_b128 v219, v[60:63] offset:1152
	s_waitcnt vmcnt(28)
	ds_write_b128 v219, v[80:83] offset:2304
	s_waitcnt vmcnt(26)
	ds_write_b128 v219, v[92:95] offset:3456
	s_waitcnt vmcnt(24)
	ds_write_b128 v219, v[100:103] offset:4608
	s_waitcnt vmcnt(22)
	ds_write_b128 v219, v[108:111] offset:5760
	s_waitcnt vmcnt(20)
	ds_write_b128 v219, v[116:119] offset:6912
	s_waitcnt vmcnt(18)
	ds_write_b128 v219, v[124:127] offset:8064
	ds_write_b128 v220, v[56:59] offset:9216
	ds_write_b128 v220, v[72:75] offset:10240
	ds_write_b128 v220, v[84:87] offset:11264
	ds_write_b128 v220, v[96:99] offset:12288
	ds_write_b128 v220, v[104:107] offset:13312
	ds_write_b128 v220, v[112:115] offset:14336
	ds_write_b128 v220, v[120:123] offset:15360
	ds_write_b128 v220, v[128:131] offset:16384
	v_readfirstlane_b32 s0, v2
	s_add_i32 s67, s77, s0
	s_cmp_eq_u32 s67, 1
	s_cselect_b32 s0, 2, 4
	s_lshl_b32 s20, s78, 6
	s_lshr_b32 s1, 16, s0
	s_sub_i32 s18, 0x80, s20
	s_lshr_b32 s0, s8, s0
	ds_read_b128 v[60:63], v228 offset:9216
	ds_read_b128 v[72:75], v229 offset:9216
	ds_read_b128 v[56:59], v230 offset:9728
	ds_read_b128 v[48:51], v231 offset:9728
	s_sub_i32 s21, s18, s0
	v_mul_u32_u24_e32 v2, s1, v173
	v_mov_b32_e32 v3, s18
	s_cmp_lg_u32 s67, 2
	v_mad_u32_u24 v3, s1, v173, v3
	s_cselect_b64 s[0:1], -1, 0
	s_cmp_lg_u32 s78, 2
	v_subrev_u32_e32 v2, s20, v2
	s_cselect_b64 s[18:19], -1, 0
	v_max_i32_e32 v80, s21, v2
	s_or_b64 s[0:1], s[0:1], s[18:19]
	v_sub_u32_e32 v2, v3, v80
	v_sub_u32_e32 v85, v176, v80
	s_mov_b64 s[14:15], -1
	s_and_b64 vcc, exec, s[0:1]
	v_cmp_le_u32_e64 s[0:1], v85, v2
	v_add_u32_e32 v86, 1, v85
	v_add_u32_e32 v84, 2, v85
	v_add_u32_e32 v83, 3, v85
	v_add_u32_e32 v82, 4, v85
	v_add_u32_e32 v81, 5, v85
	v_add_u32_e32 v80, 6, v85
	v_add_u32_e32 v3, 7, v85
	s_cbranch_vccz .LBB0_557
	s_waitcnt vmcnt(17) lgkmcnt(3)
	v_mfma_f32_16x16x32_bf16 v[92:95], v[60:63], v[132:135], 0
	ds_read_b128 v[96:99], v228 offset:13312
	ds_read_b128 v[100:103], v229 offset:13312
	v_cmp_le_u32_e32 vcc, v86, v2
	ds_read_b128 v[104:107], v230 offset:13824
	ds_read_b128 v[108:111], v231 offset:13824
	s_waitcnt vmcnt(16) lgkmcnt(6)
	v_mfma_f32_16x16x32_bf16 v[92:95], v[72:75], v[136:139], v[92:95]
	s_mov_b64 s[14:15], 0
	s_waitcnt lgkmcnt(5)
	v_mfma_f32_16x16x32_bf16 v[112:115], v[56:59], v[132:135], 0
	s_waitcnt lgkmcnt(4)
	v_mfma_f32_16x16x32_bf16 v[112:115], v[48:51], v[136:139], v[112:115]
	s_nop 2
	v_cndmask_b32_e32 v116, v217, v93, vcc
	v_cmp_le_u32_e32 vcc, v84, v2
	v_cndmask_b32_e64 v87, v217, v92, s[0:1]
	s_nop 0
	v_cndmask_b32_e32 v117, v217, v94, vcc
	v_cmp_le_u32_e32 vcc, v83, v2
	s_nop 1
	v_cndmask_b32_e32 v118, v217, v95, vcc
	s_waitcnt lgkmcnt(3)
	v_mfma_f32_16x16x32_bf16 v[92:95], v[96:99], v[132:135], 0
	v_cmp_le_u32_e32 vcc, v82, v2
	s_nop 1
	v_cndmask_b32_e32 v112, v217, v112, vcc
	v_cmp_le_u32_e32 vcc, v81, v2
	s_waitcnt lgkmcnt(2)
	v_mfma_f32_16x16x32_bf16 v[92:95], v[100:103], v[136:139], v[92:95]
	v_add_u32_e32 v101, 32, v85
	v_cndmask_b32_e32 v113, v217, v113, vcc
	v_cmp_le_u32_e32 vcc, v80, v2
	s_waitcnt lgkmcnt(1)
	v_mfma_f32_16x16x32_bf16 v[96:99], v[104:107], v[132:135], 0
	v_cndmask_b32_e32 v114, v217, v114, vcc
	v_cmp_le_u32_e32 vcc, v3, v2
	s_waitcnt lgkmcnt(0)
	v_mfma_f32_16x16x32_bf16 v[96:99], v[108:111], v[136:139], v[96:99]
	v_cndmask_b32_e32 v100, v217, v115, vcc
	v_cmp_le_u32_e32 vcc, v101, v2
	v_add_u32_e32 v101, 33, v85
	s_nop 0
	v_cndmask_b32_e32 v92, v217, v92, vcc
	v_cmp_le_u32_e32 vcc, v101, v2
	v_add_u32_e32 v101, 34, v85
	s_nop 0
	v_cndmask_b32_e32 v93, v217, v93, vcc
	v_cmp_le_u32_e32 vcc, v101, v2
	v_add_u32_e32 v101, 35, v85
	s_nop 0
	v_cndmask_b32_e32 v94, v217, v94, vcc
	v_cmp_le_u32_e32 vcc, v101, v2
	v_add_u32_e32 v101, 36, v85
	s_nop 0
	v_cndmask_b32_e32 v95, v217, v95, vcc
	v_cmp_le_u32_e32 vcc, v101, v2
	v_add_u32_e32 v101, 37, v85
	s_nop 0
	v_cndmask_b32_e32 v96, v217, v96, vcc
	v_cmp_le_u32_e32 vcc, v101, v2
	v_add_u32_e32 v101, 38, v85
	s_nop 0
	v_cndmask_b32_e32 v97, v217, v97, vcc
	v_cmp_le_u32_e32 vcc, v101, v2
	v_add_u32_e32 v101, 39, v85
	s_nop 0
	v_cndmask_b32_e32 v98, v217, v98, vcc
	v_cmp_le_u32_e32 vcc, v101, v2
	v_max3_f32 v101, v87, s62, v116
	v_max3_f32 v101, v101, v117, v118
	v_max3_f32 v101, v101, v112, v113
	v_max3_f32 v101, v101, v114, v100
	v_max3_f32 v101, v101, v92, v93
	v_max3_f32 v101, v101, v94, v95
	v_cndmask_b32_e32 v99, v217, v99, vcc
	v_max3_f32 v101, v101, v96, v97
	v_max3_f32 v101, v101, v98, v99
	ds_bpermute_b32 v102, v0, v101
	s_waitcnt lgkmcnt(0)
	v_max_f32_e32 v102, v102, v102
	v_max_f32_e32 v101, v101, v102
	ds_bpermute_b32 v102, v222, v101
	s_waitcnt lgkmcnt(0)
	v_max3_f32 v223, v226, v101, v102
	v_sub_f32_e32 v87, v87, v223
	v_exp_f32_e32 v87, v87
	v_sub_f32_e32 v102, v116, v223
	v_exp_f32_e32 v102, v102
	v_sub_f32_e32 v103, v117, v223
	v_sub_f32_e32 v92, v92, v223
	v_exp_f32_e32 v103, v103
	v_sub_f32_e32 v104, v118, v223
	v_exp_f32_e32 v130, v92
	v_sub_f32_e32 v92, v93, v223
	v_exp_f32_e32 v104, v104
	v_sub_f32_e32 v106, v112, v223
	v_exp_f32_e32 v131, v92
	v_sub_f32_e32 v92, v94, v223
	v_add_f32_e32 v105, 0, v87
	v_exp_f32_e32 v106, v106
	v_sub_f32_e32 v107, v113, v223
	v_exp_f32_e32 v140, v92
	v_sub_f32_e32 v92, v95, v223
	v_add_f32_e32 v105, v102, v105
	v_exp_f32_e32 v107, v107
	v_sub_f32_e32 v108, v114, v223
	v_exp_f32_e32 v141, v92
	v_sub_f32_e32 v92, v96, v223
	v_add_f32_e32 v105, v103, v105
	v_exp_f32_e32 v108, v108
	v_sub_f32_e32 v100, v100, v223
	v_exp_f32_e32 v142, v92
	v_sub_f32_e32 v92, v97, v223
	v_sub_f32_e32 v101, v226, v223
	v_add_f32_e32 v105, v104, v105
	v_exp_f32_e32 v100, v100
	v_exp_f32_e32 v143, v92
	v_sub_f32_e32 v92, v98, v223
	v_add_f32_e32 v105, v106, v105
	v_exp_f32_e32 v224, v92
	v_sub_f32_e32 v116, v99, v223
	v_exp_f32_e32 v128, v101
	v_cvt_pk_bf16_f32 v92, v87, v102
	v_cvt_pk_bf16_f32 v93, v103, v104
	v_cvt_pk_bf16_f32 v94, v106, v107
	v_cvt_pk_bf16_f32 v95, v108, v100
	ds_read_b64_tr_b16 v[98:99], v225 offset:576
	ds_read_b64_tr_b16 v[96:97], v225
	v_add_f32_e32 v105, v107, v105
	v_add_f32_e32 v105, v108, v105
	v_add_f32_e32 v129, v100, v105
	ds_read_b64_tr_b16 v[106:107], v225 offset:608
	ds_read_b64_tr_b16 v[104:105], v225 offset:32
	ds_read_b64_tr_b16 v[108:109], v225 offset:64
	ds_read_b64_tr_b16 v[112:113], v225 offset:96
	ds_read_b64_tr_b16 v[110:111], v225 offset:640
	ds_read_b64_tr_b16 v[114:115], v225 offset:672
	v_pk_mul_f32 v[102:103], v[170:171], v[128:129] op_sel_hi:[1,0]
	v_pk_mul_f32 v[100:101], v[168:169], v[128:129] op_sel_hi:[1,0]
	v_exp_f32_e32 v87, v116
	v_pk_mul_f32 v[118:119], v[166:167], v[128:129] op_sel_hi:[1,0]
	s_waitcnt lgkmcnt(6)
	v_mfma_f32_16x16x32_bf16 v[96:99], v[96:99], v[92:95], v[100:103]
	v_mul_f32_e64 v116, v164, v128
	v_mul_f32_e64 v117, v165, v128
	s_nop 0
	v_pk_mul_f32 v[102:103], v[158:159], v[128:129] op_sel_hi:[1,0]
	v_pk_mul_f32 v[100:101], v[156:157], v[128:129] op_sel_hi:[1,0]
	s_waitcnt lgkmcnt(4)
	s_nop 0
	v_mfma_f32_16x16x32_bf16 v[100:103], v[104:107], v[92:95], v[100:103]
	v_mul_f32_e64 v106, v162, v128
	v_mul_f32_e64 v107, v163, v128
	v_pk_mul_f32 v[104:105], v[160:161], v[128:129] op_sel_hi:[1,0]
	s_waitcnt lgkmcnt(1)
	s_nop 0
	v_mfma_f32_16x16x32_bf16 v[104:107], v[108:111], v[92:95], v[104:107]
	v_cvt_pk_bf16_f32 v108, v130, v131
	v_cvt_pk_bf16_f32 v109, v140, v141
	v_cvt_pk_bf16_f32 v110, v142, v143
	v_cvt_pk_bf16_f32 v111, v224, v87
	ds_read_b64_tr_b16 v[122:123], v225 offset:5184
	ds_read_b64_tr_b16 v[120:121], v225 offset:4608
	s_waitcnt lgkmcnt(0)
	v_mfma_f32_16x16x32_bf16 v[152:155], v[120:123], v[108:111], v[96:99]
	s_nop 2
	v_add_f32_e32 v96, v130, v129
	v_add_f32_e32 v96, v131, v96
	v_add_f32_e32 v96, v140, v96
	v_mfma_f32_16x16x32_bf16 v[92:95], v[112:115], v[92:95], v[116:119]
	ds_read_b64_tr_b16 v[114:115], v225 offset:5216
	ds_read_b64_tr_b16 v[112:113], v225 offset:4640
	s_nop 0
	ds_read_b64_tr_b16 v[116:117], v225 offset:4672
	ds_read_b64_tr_b16 v[124:125], v225 offset:4704
	ds_read_b64_tr_b16 v[118:119], v225 offset:5248
	ds_read_b64_tr_b16 v[126:127], v225 offset:5280
	v_add_f32_e32 v96, v141, v96
	v_add_f32_e32 v96, v142, v96
	v_add_f32_e32 v96, v143, v96
	s_waitcnt lgkmcnt(0)
	v_add_f32_e32 v96, v224, v96
	v_add_f32_e32 v224, v87, v96
	s_waitcnt lgkmcnt(4)
	v_mfma_f32_16x16x32_bf16 v[148:151], v[112:115], v[108:111], v[100:103]
	v_fmac_f32_e32 v224, v227, v128
	s_waitcnt lgkmcnt(1)
	v_mfma_f32_16x16x32_bf16 v[144:147], v[116:119], v[108:111], v[104:107]
	s_waitcnt lgkmcnt(0)
	v_mfma_f32_16x16x32_bf16 v[140:143], v[124:127], v[108:111], v[92:95]
